# SwiGLU epilogue: next unit's rstd partials prefetched during this unit's epilogue (no load wait at epilogue start)
# speedup vs baseline: 1.0135x; 1.0011x over previous
.LBB0_1062:
	v_and_b32_e32 v15, 15, v8
	s_add_u32 s42, s46, s36
	v_and_b32_e32 v16, 48, v8
	v_lshlrev_b32_e32 v15, 6, v15
	v_lshlrev_b32_e32 v8, 2, v8
	s_addc_u32 s43, s47, s37
	v_or_b32_e32 v17, v15, v16
	s_lshl_b32 s4, s4, 13
	v_and_b32_e32 v8, 32, v8
	v_bitop3_b32 v15, v15, v8, v16 bitop3:0x36
	v_bitop3_b32 v8, v17, s4, v8 bitop3:0xde
	s_lshl_b32 s4, s5, 12
	s_add_i32 m0, s79, 0x18000
	v_lshl_add_u64 v[6:7], v[6:7], 0, s[44:45]
	s_and_b32 s4, s4, 0x3000
	s_waitcnt vmcnt(2)
	s_barrier
	global_load_lds_dwordx4 v[6:7], off
	v_lshl_add_u64 v[4:5], v[4:5], 0, s[44:45]
	s_add_i32 m0, s79, 0x1a000
	s_add_i32 s83, s79, 0x8000
	s_add_i32 s84, s79, 0xa000
	v_or_b32_e32 v173, s4, v15
	global_load_lds_dwordx4 v[4:5], off
	v_lshl_add_u64 v[0:1], v[0:1], 0, s[44:45]
	s_mov_b32 m0, s83
	s_add_u32 s4, s2, 0x40080
	global_load_lds_dwordx4 v[0:1], off
	v_lshl_add_u64 v[0:1], v[2:3], 0, s[44:45]
	s_mov_b32 m0, s84
	s_addc_u32 s5, s3, 0
	global_load_lds_dwordx4 v[0:1], off
	s_add_i32 m0, s79, 0x1c000
	v_lshl_add_u64 v[0:1], s[4:5], 0, v[146:147]
	global_load_lds_dwordx4 v[0:1], off
	v_lshl_add_u64 v[0:1], s[4:5], 0, v[150:151]
	s_add_i32 m0, s79, 0x1e000
	s_cmpk_lt_u32 s9, 0x100
	global_load_lds_dwordx4 v[0:1], off
	s_cselect_b64 s[44:45], -1, 0
	s_abs_i32 s87, s74
	v_cvt_f32_u32_e32 v0, s87
	v_and_b32_e32 v1, 1, v9
	s_sub_i32 s4, 0, s87
	s_waitcnt vmcnt(6)
	v_rcp_iflag_f32_e32 v0, v0
	s_ashr_i32 s85, s72, 31
	s_ashr_i32 s86, s74, 31
	s_mov_b32 s88, 0
	v_mul_f32_e32 v0, 0x4f7ffffe, v0
	v_cvt_u32_f32_e32 v0, v0
	v_mov_b32_e32 v153, v177
	v_mov_b32_e32 v155, v177
	v_add_u32_e32 v175, 0, v8
	v_readfirstlane_b32 s5, v0
	v_lshlrev_b32_e32 v0, 14, v9
	v_and_b32_e32 v0, 0xffff8000, v0
	v_lshl_add_u32 v0, v10, 11, v0
	v_lshl_or_b32 v0, v1, 6, v0
	v_lshl_add_u32 v152, v11, 1, v0
	v_lshlrev_b32_e32 v0, 14, v12
	v_and_b32_e32 v0, 0xffff8000, v0
	s_mul_i32 s4, s4, s5
	v_lshl_add_u32 v0, v13, 11, v0
	v_and_b32_e32 v1, 1, v12
	s_mul_hi_u32 s4, s5, s4
	v_lshl_or_b32 v0, v1, 6, v0
	s_add_i32 s89, s5, s4
	v_lshl_add_u32 v154, v14, 1, v0
	s_mov_b64 s[46:47], s[0:1]
	s_mov_b64 s[48:49], s[2:3]
	s_barrier
	s_mov_b32 s98, 0
	s_branch .LBB0_1065

.LBB0_1087:
	v_readfirstlane_b32 s2, v179
	v_mov_b32_e32 v188, 0x358637bd
	s_ashr_i32 s1, s2, 2
	s_andn2_b32 s1, s1, 63
	s_lshl_b32 s0, s8, 8
	s_add_i32 s0, s0, s1
	v_and_or_b32 v184, v179, 15, s0
	v_ashrrev_i32_e32 v185, 31, v184
	s_cmp_lg_u32 s98, 0
	s_cbranch_scc1 .Lswg_have
	v_lshl_add_u64 v[128:129], v[184:185], 4, s[24:25]
	global_load_dwordx4 v[190:193], v[128:129], off
	global_load_dwordx4 v[194:197], v[128:129], off offset:256
	global_load_dwordx4 v[198:201], v[128:129], off offset:512
	global_load_dwordx4 v[214:217], v[128:129], off offset:768
	global_load_dwordx4 v[140:143], v[128:129], off offset:2048
	global_load_dwordx4 v[136:139], v[128:129], off offset:2304
	global_load_dwordx4 v[132:135], v[128:129], off offset:2560
	global_load_dwordx4 v[156:159], v[128:129], off offset:2816
	s_mov_b32 s0, 0x3a800000
	s_waitcnt vmcnt(0)
	v_add_f32_e32 v190, v190, v191
	v_add_f32_e32 v192, v192, v193
	v_add_f32_e32 v194, v194, v195
	v_add_f32_e32 v196, v196, v197
	v_add_f32_e32 v198, v198, v199
	v_add_f32_e32 v200, v200, v201
	v_add_f32_e32 v214, v214, v215
	v_add_f32_e32 v216, v216, v217
	v_add_f32_e32 v140, v140, v141
	v_add_f32_e32 v142, v142, v143
	v_add_f32_e32 v136, v136, v137
	v_add_f32_e32 v138, v138, v139
	v_add_f32_e32 v132, v132, v133
	v_add_f32_e32 v134, v134, v135
	v_add_f32_e32 v156, v156, v157
	v_add_f32_e32 v158, v158, v159
	v_add_f32_e32 v190, v190, v192
	v_add_f32_e32 v194, v194, v196
	v_add_f32_e32 v198, v198, v200
	v_add_f32_e32 v214, v214, v216
	v_add_f32_e32 v140, v140, v142
	v_add_f32_e32 v136, v136, v138
	v_add_f32_e32 v132, v132, v134
	v_add_f32_e32 v156, v156, v158
	v_fma_f32 v190, v190, s0, v188
	v_fma_f32 v194, v194, s0, v188
	v_fma_f32 v198, v198, s0, v188
	v_fma_f32 v214, v214, s0, v188
	v_fma_f32 v140, v140, s0, v188
	v_fma_f32 v136, v136, s0, v188
	v_fma_f32 v132, v132, s0, v188
	v_fma_f32 v156, v156, s0, v188
	v_rsq_f32_e32 v240, v190
	v_rsq_f32_e32 v241, v194
	v_rsq_f32_e32 v242, v198
	v_rsq_f32_e32 v243, v214
	v_rsq_f32_e32 v244, v140
	v_rsq_f32_e32 v245, v136
	v_rsq_f32_e32 v246, v132
	v_rsq_f32_e32 v247, v156
	s_mov_b32 s98, 1
.Lswg_have:
	s_cmp_lg_u64 s[38:39], 0
	s_cselect_b32 s0, s91, s8
	s_lshl_b32 s0, s0, 8
	s_add_i32 s0, s0, s1
	v_and_or_b32 v130, v179, 15, s0
	v_ashrrev_i32_e32 v131, 31, v130
	v_lshl_add_u64 v[128:129], v[130:131], 4, s[24:25]
	global_load_dwordx4 v[190:193], v[128:129], off
	global_load_dwordx4 v[194:197], v[128:129], off offset:256
	global_load_dwordx4 v[198:201], v[128:129], off offset:512
	global_load_dwordx4 v[214:217], v[128:129], off offset:768
	global_load_dwordx4 v[140:143], v[128:129], off offset:2048
	global_load_dwordx4 v[136:139], v[128:129], off offset:2304
	global_load_dwordx4 v[132:135], v[128:129], off offset:2560
	global_load_dwordx4 v[156:159], v[128:129], off offset:2816
	s_movk_i32 s8, 0x1600
	v_mov_b64_e32 v[186:187], s[42:43]
	s_lshl_b32 s0, s33, 8
	s_and_b32 s1, s2, 0xc0
	v_mad_i64_i32 v[186:187], s[4:5], v184, s8, v[186:187]
	s_add_i32 s0, s0, s1
	v_and_b32_e32 v176, 48, v179
	v_add_u32_e32 v176, s0, v176
	s_mov_b32 s2, 0xbfb8aa3b
	v_lshl_add_u64 v[186:187], v[186:187], 0, v[176:177]
	s_mov_b32 s0, 1.0
	v_pk_mul_f32 v[124:125], v[124:125], v[240:241] op_sel_hi:[1,0]
	v_pk_mul_f32 v[126:127], v[126:127], v[240:241] op_sel_hi:[1,0]
	v_pk_mul_f32 v[116:117], v[116:117], v[240:241] op_sel_hi:[1,0]
	v_pk_mul_f32 v[118:119], v[118:119], v[240:241] op_sel_hi:[1,0]
	v_pk_mul_f32 v[120:121], v[120:121], v[240:241] op_sel_hi:[1,0]
	v_pk_mul_f32 v[122:123], v[122:123], v[240:241] op_sel_hi:[1,0]
	v_pk_mul_f32 v[112:113], v[112:113], v[240:241] op_sel_hi:[1,0]
	v_pk_mul_f32 v[114:115], v[114:115], v[240:241] op_sel_hi:[1,0]
	v_pk_mul_f32 v[120:121], v[124:125], v[120:121]
	v_pk_mul_f32 v[122:123], v[126:127], v[122:123]
	v_pk_mul_f32 v[112:113], v[116:117], v[112:113]
	v_pk_mul_f32 v[114:115], v[118:119], v[114:115]
	v_pk_mul_f32 v[124:125], v[124:125], s[2:3] op_sel_hi:[1,0]
	v_pk_mul_f32 v[126:127], v[126:127], s[2:3] op_sel_hi:[1,0]
	v_pk_mul_f32 v[116:117], v[116:117], s[2:3] op_sel_hi:[1,0]
	v_pk_mul_f32 v[118:119], v[118:119], s[2:3] op_sel_hi:[1,0]
	v_exp_f32_e32 v124, v124
	v_exp_f32_e32 v125, v125
	v_exp_f32_e32 v126, v126
	v_exp_f32_e32 v127, v127
	v_exp_f32_e32 v116, v116
	v_exp_f32_e32 v117, v117
	v_exp_f32_e32 v118, v118
	v_exp_f32_e32 v119, v119
	v_pk_add_f32 v[124:125], v[124:125], s[0:1] op_sel_hi:[1,0]
	v_pk_add_f32 v[126:127], v[126:127], s[0:1] op_sel_hi:[1,0]
	v_pk_add_f32 v[116:117], v[116:117], s[0:1] op_sel_hi:[1,0]
	v_pk_add_f32 v[118:119], v[118:119], s[0:1] op_sel_hi:[1,0]
	v_rcp_f32_e32 v124, v124
	v_rcp_f32_e32 v125, v125
	v_rcp_f32_e32 v126, v126
	v_rcp_f32_e32 v127, v127
	v_rcp_f32_e32 v116, v116
	v_rcp_f32_e32 v117, v117
	v_rcp_f32_e32 v118, v118
	v_rcp_f32_e32 v119, v119
	v_pk_mul_f32 v[120:121], v[120:121], v[124:125]
	v_pk_mul_f32 v[122:123], v[122:123], v[126:127]
	v_pk_mul_f32 v[112:113], v[112:113], v[116:117]
	v_pk_mul_f32 v[114:115], v[114:115], v[118:119]
	v_cvt_pk_bf16_f32 v124, v120, v121
	v_cvt_pk_bf16_f32 v125, v122, v123
	v_cvt_pk_bf16_f32 v126, v112, v113
	v_cvt_pk_bf16_f32 v127, v114, v115
	global_store_dwordx4 v[186:187], v[124:127], off
	v_pk_mul_f32 v[108:109], v[108:109], v[240:241] op_sel:[0,1]
	v_pk_mul_f32 v[110:111], v[110:111], v[240:241] op_sel:[0,1]
	v_pk_mul_f32 v[100:101], v[100:101], v[240:241] op_sel:[0,1]
	v_pk_mul_f32 v[102:103], v[102:103], v[240:241] op_sel:[0,1]
	v_pk_mul_f32 v[104:105], v[104:105], v[240:241] op_sel:[0,1]
	v_pk_mul_f32 v[106:107], v[106:107], v[240:241] op_sel:[0,1]
	v_pk_mul_f32 v[96:97], v[96:97], v[240:241] op_sel:[0,1]
	v_pk_mul_f32 v[98:99], v[98:99], v[240:241] op_sel:[0,1]
	v_pk_mul_f32 v[104:105], v[108:109], v[104:105]
	v_pk_mul_f32 v[106:107], v[110:111], v[106:107]
	v_pk_mul_f32 v[96:97], v[100:101], v[96:97]
	v_pk_mul_f32 v[98:99], v[102:103], v[98:99]
	v_pk_mul_f32 v[108:109], v[108:109], s[2:3] op_sel_hi:[1,0]
	v_pk_mul_f32 v[110:111], v[110:111], s[2:3] op_sel_hi:[1,0]
	v_pk_mul_f32 v[100:101], v[100:101], s[2:3] op_sel_hi:[1,0]
	v_pk_mul_f32 v[102:103], v[102:103], s[2:3] op_sel_hi:[1,0]
	v_exp_f32_e32 v108, v108
	v_exp_f32_e32 v109, v109
	v_exp_f32_e32 v110, v110
	v_exp_f32_e32 v111, v111
	v_exp_f32_e32 v100, v100
	v_exp_f32_e32 v101, v101
	v_exp_f32_e32 v102, v102
	v_exp_f32_e32 v103, v103
	v_pk_add_f32 v[108:109], v[108:109], s[0:1] op_sel_hi:[1,0]
	v_pk_add_f32 v[110:111], v[110:111], s[0:1] op_sel_hi:[1,0]
	v_pk_add_f32 v[100:101], v[100:101], s[0:1] op_sel_hi:[1,0]
	v_pk_add_f32 v[102:103], v[102:103], s[0:1] op_sel_hi:[1,0]
	v_rcp_f32_e32 v108, v108
	v_rcp_f32_e32 v109, v109
	v_rcp_f32_e32 v110, v110
	v_rcp_f32_e32 v111, v111
	v_rcp_f32_e32 v100, v100
	v_rcp_f32_e32 v101, v101
	v_rcp_f32_e32 v102, v102
	v_rcp_f32_e32 v103, v103
	s_mov_b64 s[4:5], 0x16000
	v_lshl_add_u64 v[130:131], v[186:187], 0, s[4:5]
	v_pk_mul_f32 v[104:105], v[104:105], v[108:109]
	v_pk_mul_f32 v[106:107], v[106:107], v[110:111]
	v_pk_mul_f32 v[96:97], v[96:97], v[100:101]
	v_pk_mul_f32 v[98:99], v[98:99], v[102:103]
	v_cvt_pk_bf16_f32 v108, v104, v105
	v_cvt_pk_bf16_f32 v109, v106, v107
	v_cvt_pk_bf16_f32 v110, v96, v97
	v_cvt_pk_bf16_f32 v111, v98, v99
	global_store_dwordx4 v[130:131], v[108:111], off
	v_pk_mul_f32 v[92:93], v[92:93], v[242:243] op_sel_hi:[1,0]
	v_pk_mul_f32 v[94:95], v[94:95], v[242:243] op_sel_hi:[1,0]
	v_pk_mul_f32 v[84:85], v[84:85], v[242:243] op_sel_hi:[1,0]
	v_pk_mul_f32 v[86:87], v[86:87], v[242:243] op_sel_hi:[1,0]
	v_pk_mul_f32 v[88:89], v[88:89], v[242:243] op_sel_hi:[1,0]
	v_pk_mul_f32 v[90:91], v[90:91], v[242:243] op_sel_hi:[1,0]
	v_pk_mul_f32 v[80:81], v[80:81], v[242:243] op_sel_hi:[1,0]
	v_pk_mul_f32 v[82:83], v[82:83], v[242:243] op_sel_hi:[1,0]
	v_pk_mul_f32 v[88:89], v[92:93], v[88:89]
	v_pk_mul_f32 v[90:91], v[94:95], v[90:91]
	v_pk_mul_f32 v[80:81], v[84:85], v[80:81]
	v_pk_mul_f32 v[82:83], v[86:87], v[82:83]
	v_pk_mul_f32 v[92:93], v[92:93], s[2:3] op_sel_hi:[1,0]
	v_pk_mul_f32 v[94:95], v[94:95], s[2:3] op_sel_hi:[1,0]
	v_pk_mul_f32 v[84:85], v[84:85], s[2:3] op_sel_hi:[1,0]
	v_pk_mul_f32 v[86:87], v[86:87], s[2:3] op_sel_hi:[1,0]
	v_exp_f32_e32 v92, v92
	v_exp_f32_e32 v93, v93
	v_exp_f32_e32 v94, v94
	v_exp_f32_e32 v95, v95
	v_exp_f32_e32 v84, v84
	v_exp_f32_e32 v85, v85
	v_exp_f32_e32 v86, v86
	v_exp_f32_e32 v87, v87
	v_pk_add_f32 v[92:93], v[92:93], s[0:1] op_sel_hi:[1,0]
	v_pk_add_f32 v[94:95], v[94:95], s[0:1] op_sel_hi:[1,0]
	v_pk_add_f32 v[84:85], v[84:85], s[0:1] op_sel_hi:[1,0]
	v_pk_add_f32 v[86:87], v[86:87], s[0:1] op_sel_hi:[1,0]
	v_rcp_f32_e32 v92, v92
	v_rcp_f32_e32 v93, v93
	v_rcp_f32_e32 v94, v94
	v_rcp_f32_e32 v95, v95
	v_rcp_f32_e32 v84, v84
	v_rcp_f32_e32 v85, v85
	v_rcp_f32_e32 v86, v86
	v_rcp_f32_e32 v87, v87
	s_mov_b64 s[4:5], 0x2c000
	v_lshl_add_u64 v[128:129], v[186:187], 0, s[4:5]
	v_pk_mul_f32 v[88:89], v[88:89], v[92:93]
	v_pk_mul_f32 v[90:91], v[90:91], v[94:95]
	v_pk_mul_f32 v[80:81], v[80:81], v[84:85]
	v_pk_mul_f32 v[82:83], v[82:83], v[86:87]
	v_cvt_pk_bf16_f32 v92, v88, v89
	v_cvt_pk_bf16_f32 v93, v90, v91
	v_cvt_pk_bf16_f32 v94, v80, v81
	v_cvt_pk_bf16_f32 v95, v82, v83
	global_store_dwordx4 v[128:129], v[92:95], off
	v_pk_mul_f32 v[76:77], v[76:77], v[242:243] op_sel:[0,1]
	v_pk_mul_f32 v[78:79], v[78:79], v[242:243] op_sel:[0,1]
	v_pk_mul_f32 v[68:69], v[68:69], v[242:243] op_sel:[0,1]
	v_pk_mul_f32 v[70:71], v[70:71], v[242:243] op_sel:[0,1]
	v_pk_mul_f32 v[72:73], v[72:73], v[242:243] op_sel:[0,1]
	v_pk_mul_f32 v[74:75], v[74:75], v[242:243] op_sel:[0,1]
	v_pk_mul_f32 v[64:65], v[64:65], v[242:243] op_sel:[0,1]
	v_pk_mul_f32 v[66:67], v[66:67], v[242:243] op_sel:[0,1]
	v_pk_mul_f32 v[72:73], v[76:77], v[72:73]
	v_pk_mul_f32 v[74:75], v[78:79], v[74:75]
	v_pk_mul_f32 v[64:65], v[68:69], v[64:65]
	v_pk_mul_f32 v[66:67], v[70:71], v[66:67]
	v_pk_mul_f32 v[76:77], v[76:77], s[2:3] op_sel_hi:[1,0]
	v_pk_mul_f32 v[78:79], v[78:79], s[2:3] op_sel_hi:[1,0]
	v_pk_mul_f32 v[68:69], v[68:69], s[2:3] op_sel_hi:[1,0]
	v_pk_mul_f32 v[70:71], v[70:71], s[2:3] op_sel_hi:[1,0]
	v_exp_f32_e32 v76, v76
	v_exp_f32_e32 v77, v77
	v_exp_f32_e32 v78, v78
	v_exp_f32_e32 v79, v79
	v_exp_f32_e32 v68, v68
	v_exp_f32_e32 v69, v69
	v_exp_f32_e32 v70, v70
	v_exp_f32_e32 v71, v71
	v_pk_add_f32 v[76:77], v[76:77], s[0:1] op_sel_hi:[1,0]
	v_pk_add_f32 v[78:79], v[78:79], s[0:1] op_sel_hi:[1,0]
	v_pk_add_f32 v[68:69], v[68:69], s[0:1] op_sel_hi:[1,0]
	v_pk_add_f32 v[70:71], v[70:71], s[0:1] op_sel_hi:[1,0]
	v_rcp_f32_e32 v76, v76
	v_rcp_f32_e32 v77, v77
	v_rcp_f32_e32 v78, v78
	v_rcp_f32_e32 v79, v79
	v_rcp_f32_e32 v68, v68
	v_rcp_f32_e32 v69, v69
	v_rcp_f32_e32 v70, v70
	v_rcp_f32_e32 v71, v71
	s_mov_b64 s[4:5], 0x42000
	v_lshl_add_u64 v[130:131], v[186:187], 0, s[4:5]
	v_pk_mul_f32 v[72:73], v[72:73], v[76:77]
	v_pk_mul_f32 v[74:75], v[74:75], v[78:79]
	v_pk_mul_f32 v[64:65], v[64:65], v[68:69]
	v_pk_mul_f32 v[66:67], v[66:67], v[70:71]
	v_cvt_pk_bf16_f32 v76, v72, v73
	v_cvt_pk_bf16_f32 v77, v74, v75
	v_cvt_pk_bf16_f32 v78, v64, v65
	v_cvt_pk_bf16_f32 v79, v66, v67
	global_store_dwordx4 v[130:131], v[76:79], off
	v_pk_mul_f32 v[60:61], v[60:61], v[244:245] op_sel_hi:[1,0]
	v_pk_mul_f32 v[62:63], v[62:63], v[244:245] op_sel_hi:[1,0]
	v_pk_mul_f32 v[52:53], v[52:53], v[244:245] op_sel_hi:[1,0]
	v_pk_mul_f32 v[54:55], v[54:55], v[244:245] op_sel_hi:[1,0]
	v_pk_mul_f32 v[56:57], v[56:57], v[244:245] op_sel_hi:[1,0]
	v_pk_mul_f32 v[58:59], v[58:59], v[244:245] op_sel_hi:[1,0]
	v_pk_mul_f32 v[48:49], v[48:49], v[244:245] op_sel_hi:[1,0]
	v_pk_mul_f32 v[50:51], v[50:51], v[244:245] op_sel_hi:[1,0]
	v_pk_mul_f32 v[56:57], v[60:61], v[56:57]
	v_pk_mul_f32 v[58:59], v[62:63], v[58:59]
	v_pk_mul_f32 v[48:49], v[52:53], v[48:49]
	v_pk_mul_f32 v[50:51], v[54:55], v[50:51]
	v_pk_mul_f32 v[60:61], v[60:61], s[2:3] op_sel_hi:[1,0]
	v_pk_mul_f32 v[62:63], v[62:63], s[2:3] op_sel_hi:[1,0]
	v_pk_mul_f32 v[52:53], v[52:53], s[2:3] op_sel_hi:[1,0]
	v_pk_mul_f32 v[54:55], v[54:55], s[2:3] op_sel_hi:[1,0]
	v_exp_f32_e32 v60, v60
	v_exp_f32_e32 v61, v61
	v_exp_f32_e32 v62, v62
	v_exp_f32_e32 v63, v63
	v_exp_f32_e32 v52, v52
	v_exp_f32_e32 v53, v53
	v_exp_f32_e32 v54, v54
	v_exp_f32_e32 v55, v55
	v_pk_add_f32 v[60:61], v[60:61], s[0:1] op_sel_hi:[1,0]
	v_pk_add_f32 v[62:63], v[62:63], s[0:1] op_sel_hi:[1,0]
	v_pk_add_f32 v[52:53], v[52:53], s[0:1] op_sel_hi:[1,0]
	v_pk_add_f32 v[54:55], v[54:55], s[0:1] op_sel_hi:[1,0]
	v_rcp_f32_e32 v60, v60
	v_rcp_f32_e32 v61, v61
	v_rcp_f32_e32 v62, v62
	v_rcp_f32_e32 v63, v63
	v_rcp_f32_e32 v52, v52
	v_rcp_f32_e32 v53, v53
	v_rcp_f32_e32 v54, v54
	v_rcp_f32_e32 v55, v55
	s_mov_b64 s[4:5], 0xb0000
	v_lshl_add_u64 v[128:129], v[186:187], 0, s[4:5]
	v_pk_mul_f32 v[56:57], v[56:57], v[60:61]
	v_pk_mul_f32 v[58:59], v[58:59], v[62:63]
	v_pk_mul_f32 v[48:49], v[48:49], v[52:53]
	v_pk_mul_f32 v[50:51], v[50:51], v[54:55]
	v_cvt_pk_bf16_f32 v60, v56, v57
	v_cvt_pk_bf16_f32 v61, v58, v59
	v_cvt_pk_bf16_f32 v62, v48, v49
	v_cvt_pk_bf16_f32 v63, v50, v51
	global_store_dwordx4 v[128:129], v[60:63], off
	v_pk_mul_f32 v[44:45], v[44:45], v[244:245] op_sel:[0,1]
	v_pk_mul_f32 v[46:47], v[46:47], v[244:245] op_sel:[0,1]
	v_pk_mul_f32 v[36:37], v[36:37], v[244:245] op_sel:[0,1]
	v_pk_mul_f32 v[38:39], v[38:39], v[244:245] op_sel:[0,1]
	v_pk_mul_f32 v[40:41], v[40:41], v[244:245] op_sel:[0,1]
	v_pk_mul_f32 v[42:43], v[42:43], v[244:245] op_sel:[0,1]
	v_pk_mul_f32 v[32:33], v[32:33], v[244:245] op_sel:[0,1]
	v_pk_mul_f32 v[34:35], v[34:35], v[244:245] op_sel:[0,1]
	v_pk_mul_f32 v[40:41], v[44:45], v[40:41]
	v_pk_mul_f32 v[42:43], v[46:47], v[42:43]
	v_pk_mul_f32 v[32:33], v[36:37], v[32:33]
	v_pk_mul_f32 v[34:35], v[38:39], v[34:35]
	v_pk_mul_f32 v[44:45], v[44:45], s[2:3] op_sel_hi:[1,0]
	v_pk_mul_f32 v[46:47], v[46:47], s[2:3] op_sel_hi:[1,0]
	v_pk_mul_f32 v[36:37], v[36:37], s[2:3] op_sel_hi:[1,0]
	v_pk_mul_f32 v[38:39], v[38:39], s[2:3] op_sel_hi:[1,0]
	v_exp_f32_e32 v44, v44
	v_exp_f32_e32 v45, v45
	v_exp_f32_e32 v46, v46
	v_exp_f32_e32 v47, v47
	v_exp_f32_e32 v36, v36
	v_exp_f32_e32 v37, v37
	v_exp_f32_e32 v38, v38
	v_exp_f32_e32 v39, v39
	v_pk_add_f32 v[44:45], v[44:45], s[0:1] op_sel_hi:[1,0]
	v_pk_add_f32 v[46:47], v[46:47], s[0:1] op_sel_hi:[1,0]
	v_pk_add_f32 v[36:37], v[36:37], s[0:1] op_sel_hi:[1,0]
	v_pk_add_f32 v[38:39], v[38:39], s[0:1] op_sel_hi:[1,0]
	v_rcp_f32_e32 v44, v44
	v_rcp_f32_e32 v45, v45
	v_rcp_f32_e32 v46, v46
	v_rcp_f32_e32 v47, v47
	v_rcp_f32_e32 v36, v36
	v_rcp_f32_e32 v37, v37
	v_rcp_f32_e32 v38, v38
	v_rcp_f32_e32 v39, v39
	s_mov_b64 s[4:5], 0xc6000
	v_lshl_add_u64 v[130:131], v[186:187], 0, s[4:5]
	v_pk_mul_f32 v[40:41], v[40:41], v[44:45]
	v_pk_mul_f32 v[42:43], v[42:43], v[46:47]
	v_pk_mul_f32 v[32:33], v[32:33], v[36:37]
	v_pk_mul_f32 v[34:35], v[34:35], v[38:39]
	v_cvt_pk_bf16_f32 v44, v40, v41
	v_cvt_pk_bf16_f32 v45, v42, v43
	v_cvt_pk_bf16_f32 v46, v32, v33
	v_cvt_pk_bf16_f32 v47, v34, v35
	global_store_dwordx4 v[130:131], v[44:47], off
	v_pk_mul_f32 v[28:29], v[28:29], v[246:247] op_sel_hi:[1,0]
	v_pk_mul_f32 v[30:31], v[30:31], v[246:247] op_sel_hi:[1,0]
	v_pk_mul_f32 v[20:21], v[20:21], v[246:247] op_sel_hi:[1,0]
	v_pk_mul_f32 v[22:23], v[22:23], v[246:247] op_sel_hi:[1,0]
	v_pk_mul_f32 v[24:25], v[24:25], v[246:247] op_sel_hi:[1,0]
	v_pk_mul_f32 v[26:27], v[26:27], v[246:247] op_sel_hi:[1,0]
	v_pk_mul_f32 v[16:17], v[16:17], v[246:247] op_sel_hi:[1,0]
	v_pk_mul_f32 v[18:19], v[18:19], v[246:247] op_sel_hi:[1,0]
	v_pk_mul_f32 v[24:25], v[28:29], v[24:25]
	v_pk_mul_f32 v[26:27], v[30:31], v[26:27]
	v_pk_mul_f32 v[16:17], v[20:21], v[16:17]
	v_pk_mul_f32 v[18:19], v[22:23], v[18:19]
	v_pk_mul_f32 v[28:29], v[28:29], s[2:3] op_sel_hi:[1,0]
	v_pk_mul_f32 v[30:31], v[30:31], s[2:3] op_sel_hi:[1,0]
	v_pk_mul_f32 v[20:21], v[20:21], s[2:3] op_sel_hi:[1,0]
	v_pk_mul_f32 v[22:23], v[22:23], s[2:3] op_sel_hi:[1,0]
	v_exp_f32_e32 v28, v28
	v_exp_f32_e32 v29, v29
	v_exp_f32_e32 v30, v30
	v_exp_f32_e32 v31, v31
	v_exp_f32_e32 v20, v20
	v_exp_f32_e32 v21, v21
	v_exp_f32_e32 v22, v22
	v_exp_f32_e32 v23, v23
	v_pk_add_f32 v[28:29], v[28:29], s[0:1] op_sel_hi:[1,0]
	v_pk_add_f32 v[30:31], v[30:31], s[0:1] op_sel_hi:[1,0]
	v_pk_add_f32 v[20:21], v[20:21], s[0:1] op_sel_hi:[1,0]
	v_pk_add_f32 v[22:23], v[22:23], s[0:1] op_sel_hi:[1,0]
	v_rcp_f32_e32 v28, v28
	v_rcp_f32_e32 v29, v29
	v_rcp_f32_e32 v30, v30
	v_rcp_f32_e32 v31, v31
	v_rcp_f32_e32 v20, v20
	v_rcp_f32_e32 v21, v21
	v_rcp_f32_e32 v22, v22
	v_rcp_f32_e32 v23, v23
	s_mov_b64 s[4:5], 0xdc000
	v_lshl_add_u64 v[128:129], v[186:187], 0, s[4:5]
	v_pk_mul_f32 v[24:25], v[24:25], v[28:29]
	v_pk_mul_f32 v[26:27], v[26:27], v[30:31]
	v_pk_mul_f32 v[16:17], v[16:17], v[20:21]
	v_pk_mul_f32 v[18:19], v[18:19], v[22:23]
	v_cvt_pk_bf16_f32 v28, v24, v25
	v_cvt_pk_bf16_f32 v29, v26, v27
	v_cvt_pk_bf16_f32 v30, v16, v17
	v_cvt_pk_bf16_f32 v31, v18, v19
	global_store_dwordx4 v[128:129], v[28:31], off
	v_pk_mul_f32 v[12:13], v[12:13], v[246:247] op_sel:[0,1]
	v_pk_mul_f32 v[14:15], v[14:15], v[246:247] op_sel:[0,1]
	v_pk_mul_f32 v[4:5], v[4:5], v[246:247] op_sel:[0,1]
	v_pk_mul_f32 v[6:7], v[6:7], v[246:247] op_sel:[0,1]
	v_pk_mul_f32 v[8:9], v[8:9], v[246:247] op_sel:[0,1]
	v_pk_mul_f32 v[10:11], v[10:11], v[246:247] op_sel:[0,1]
	v_pk_mul_f32 v[0:1], v[0:1], v[246:247] op_sel:[0,1]
	v_pk_mul_f32 v[2:3], v[2:3], v[246:247] op_sel:[0,1]
	v_pk_mul_f32 v[8:9], v[12:13], v[8:9]
	v_pk_mul_f32 v[10:11], v[14:15], v[10:11]
	v_pk_mul_f32 v[0:1], v[4:5], v[0:1]
	v_pk_mul_f32 v[2:3], v[6:7], v[2:3]
	v_pk_mul_f32 v[12:13], v[12:13], s[2:3] op_sel_hi:[1,0]
	v_pk_mul_f32 v[14:15], v[14:15], s[2:3] op_sel_hi:[1,0]
	v_pk_mul_f32 v[4:5], v[4:5], s[2:3] op_sel_hi:[1,0]
	v_pk_mul_f32 v[6:7], v[6:7], s[2:3] op_sel_hi:[1,0]
	v_exp_f32_e32 v12, v12
	v_exp_f32_e32 v13, v13
	v_exp_f32_e32 v14, v14
	v_exp_f32_e32 v15, v15
	v_exp_f32_e32 v4, v4
	v_exp_f32_e32 v5, v5
	v_exp_f32_e32 v6, v6
	v_exp_f32_e32 v7, v7
	v_pk_add_f32 v[12:13], v[12:13], s[0:1] op_sel_hi:[1,0]
	v_pk_add_f32 v[14:15], v[14:15], s[0:1] op_sel_hi:[1,0]
	v_pk_add_f32 v[4:5], v[4:5], s[0:1] op_sel_hi:[1,0]
	v_pk_add_f32 v[6:7], v[6:7], s[0:1] op_sel_hi:[1,0]
	v_rcp_f32_e32 v12, v12
	v_rcp_f32_e32 v13, v13
	v_rcp_f32_e32 v14, v14
	v_rcp_f32_e32 v15, v15
	v_rcp_f32_e32 v4, v4
	v_rcp_f32_e32 v5, v5
	v_rcp_f32_e32 v6, v6
	v_rcp_f32_e32 v7, v7
	s_mov_b64 s[4:5], 0xf2000
	v_lshl_add_u64 v[130:131], v[186:187], 0, s[4:5]
	v_pk_mul_f32 v[8:9], v[8:9], v[12:13]
	v_pk_mul_f32 v[10:11], v[10:11], v[14:15]
	v_pk_mul_f32 v[0:1], v[0:1], v[4:5]
	v_pk_mul_f32 v[2:3], v[2:3], v[6:7]
	v_cvt_pk_bf16_f32 v12, v8, v9
	v_cvt_pk_bf16_f32 v13, v10, v11
	v_cvt_pk_bf16_f32 v14, v0, v1
	v_cvt_pk_bf16_f32 v15, v2, v3
	global_store_dwordx4 v[130:131], v[12:15], off
	s_mov_b32 s8, 0x3a800000
	s_waitcnt vmcnt(8)
	v_add_f32_e32 v190, v190, v191
	v_add_f32_e32 v192, v192, v193
	v_add_f32_e32 v194, v194, v195
	v_add_f32_e32 v196, v196, v197
	v_add_f32_e32 v198, v198, v199
	v_add_f32_e32 v200, v200, v201
	v_add_f32_e32 v214, v214, v215
	v_add_f32_e32 v216, v216, v217
	v_add_f32_e32 v140, v140, v141
	v_add_f32_e32 v142, v142, v143
	v_add_f32_e32 v136, v136, v137
	v_add_f32_e32 v138, v138, v139
	v_add_f32_e32 v132, v132, v133
	v_add_f32_e32 v134, v134, v135
	v_add_f32_e32 v156, v156, v157
	v_add_f32_e32 v158, v158, v159
	v_add_f32_e32 v190, v190, v192
	v_add_f32_e32 v194, v194, v196
	v_add_f32_e32 v198, v198, v200
	v_add_f32_e32 v214, v214, v216
	v_add_f32_e32 v140, v140, v142
	v_add_f32_e32 v136, v136, v138
	v_add_f32_e32 v132, v132, v134
	v_add_f32_e32 v156, v156, v158
	v_fma_f32 v190, v190, s8, v188
	v_fma_f32 v194, v194, s8, v188
	v_fma_f32 v198, v198, s8, v188
	v_fma_f32 v214, v214, s8, v188
	v_fma_f32 v140, v140, s8, v188
	v_fma_f32 v136, v136, s8, v188
	v_fma_f32 v132, v132, s8, v188
	v_fma_f32 v156, v156, s8, v188
	v_rsq_f32_e32 v240, v190
	v_rsq_f32_e32 v241, v194
	v_rsq_f32_e32 v242, v198
	v_rsq_f32_e32 v243, v214
	v_rsq_f32_e32 v244, v140
	v_rsq_f32_e32 v245, v136
	v_rsq_f32_e32 v246, v132
	v_rsq_f32_e32 v247, v156
	s_mov_b64 s[0:1], -1
	s_andn2_b64 vcc, exec, s[38:39]
	s_cbranch_vccnz .LBB0_1064
	s_andn2_b64 vcc, exec, s[40:41]
	s_cbranch_vccnz .LBB0_1063
	s_barrier
	s_branch .LBB0_1063
